# attention tile loop: coarser LDS waits (one lgkmcnt per key group of 3 K fragments, one per 2 V fragments): 12 fewer s_waitcnt per tile
# speedup vs baseline: 1.0130x; 1.0130x over previous
.LBB0_175:
	s_barrier
	ds_read_b128 v[162:165], v104
	ds_read_b128 v[166:169], v104 offset:64
	ds_read_b128 v[170:173], v104 offset:128
	ds_read_b128 v[174:177], v104 offset:3584
	ds_read_b128 v[178:181], v104 offset:3648
	ds_read_b128 v[182:185], v104 offset:3712
	ds_read_b128 v[186:189], v104 offset:7168
	ds_read_b128 v[214:217], v104 offset:7232
	ds_read_b128 v[218:221], v104 offset:7296
	ds_read_b128 v[222:225], v104 offset:10752
	ds_read_b128 v[226:229], v104 offset:10816
	ds_read_b128 v[230:233], v104 offset:10880
	global_load_dwordx4 v[72:75], v[136:137], off
	global_load_dwordx4 v[68:71], v[134:135], off
	global_load_dwordx4 v[64:67], v[132:133], off
	s_and_b32 s21, s7, 15
	s_cbranch_scc0 .Lattn_refresh
	s_waitcnt lgkmcnt(9)
	v_mfma_f32_16x16x32_bf16 v[92:95], v[162:165], v[0:3], v[148:151]
	v_mfma_f32_16x16x32_bf16 v[76:79], v[162:165], v[8:11], v[152:155]
	ds_read_b64 v[234:235], v147 offset:14336
	ds_read_b64 v[236:237], v147 offset:14368
	v_mfma_f32_16x16x32_bf16 v[92:95], v[166:169], v[4:7], v[92:95]
	v_mfma_f32_16x16x32_bf16 v[76:79], v[166:169], v[12:15], v[76:79]
	ds_read_b64 v[238:239], v147 offset:14400
	ds_read_b64 v[240:241], v147 offset:14432
	v_mfma_f32_16x16x32_bf16 v[92:95], v[170:173], v[16:19], v[92:95]
	v_mfma_f32_16x16x32_bf16 v[76:79], v[170:173], v[20:23], v[76:79]
	ds_read_b64 v[242:243], v147 offset:16640
	ds_read_b64 v[244:245], v147 offset:16672
	s_waitcnt lgkmcnt(12)
	v_mfma_f32_16x16x32_bf16 v[96:99], v[174:177], v[0:3], v[148:151]
	v_mfma_f32_16x16x32_bf16 v[80:83], v[174:177], v[8:11], v[152:155]
	ds_read_b64 v[246:247], v147 offset:16704
	v_mfma_f32_16x16x32_bf16 v[96:99], v[178:181], v[4:7], v[96:99]
	v_mfma_f32_16x16x32_bf16 v[80:83], v[178:181], v[12:15], v[80:83]
	ds_read_b64 v[248:249], v147 offset:16736
	v_mfma_f32_16x16x32_bf16 v[96:99], v[182:185], v[16:19], v[96:99]
	v_mfma_f32_16x16x32_bf16 v[80:83], v[182:185], v[20:23], v[80:83]
	ds_read_b64 v[162:163], v147 offset:18944
	s_waitcnt lgkmcnt(12)
	v_mfma_f32_16x16x32_bf16 v[100:103], v[186:189], v[0:3], v[148:151]
	v_mfma_f32_16x16x32_bf16 v[84:87], v[186:189], v[8:11], v[152:155]
	ds_read_b64 v[164:165], v147 offset:18976
	v_mfma_f32_16x16x32_bf16 v[100:103], v[214:217], v[4:7], v[100:103]
	v_mfma_f32_16x16x32_bf16 v[84:87], v[214:217], v[12:15], v[84:87]
	ds_read_b64 v[166:167], v147 offset:19008
	v_mfma_f32_16x16x32_bf16 v[100:103], v[218:221], v[16:19], v[100:103]
	v_mfma_f32_16x16x32_bf16 v[84:87], v[218:221], v[20:23], v[84:87]
	ds_read_b64 v[168:169], v147 offset:19040
	s_waitcnt lgkmcnt(12)
	v_mfma_f32_16x16x32_bf16 v[104:107], v[222:225], v[0:3], v[148:151]
	v_mfma_f32_16x16x32_bf16 v[88:91], v[222:225], v[8:11], v[152:155]
	ds_read_b64 v[170:171], v147 offset:21248
	v_mfma_f32_16x16x32_bf16 v[104:107], v[226:229], v[4:7], v[104:107]
	v_mfma_f32_16x16x32_bf16 v[88:91], v[226:229], v[12:15], v[88:91]
	ds_read_b64 v[172:173], v147 offset:21280
	v_mfma_f32_16x16x32_bf16 v[104:107], v[230:233], v[16:19], v[104:107]
	v_mfma_f32_16x16x32_bf16 v[88:91], v[230:233], v[20:23], v[88:91]
	s_waitcnt lgkmcnt(13)
	ds_read_b64 v[174:175], v147 offset:21312
	ds_read_b64 v[176:177], v147 offset:21344

.Lattn_skipw:
	s_waitcnt lgkmcnt(14)
	v_mfma_f32_16x16x32_bf16 v[60:63], v[234:237], v[92:95], v[60:63]
	v_mfma_f32_16x16x32_bf16 v[56:59], v[234:237], v[76:79], v[56:59]
	v_mfma_f32_16x16x32_bf16 v[60:63], v[238:241], v[96:99], v[60:63]
	v_mfma_f32_16x16x32_bf16 v[56:59], v[238:241], v[80:83], v[56:59]
	s_waitcnt lgkmcnt(10)
	v_mfma_f32_16x16x32_bf16 v[52:55], v[242:245], v[92:95], v[52:55]
	v_mfma_f32_16x16x32_bf16 v[48:51], v[242:245], v[76:79], v[48:51]
	v_mfma_f32_16x16x32_bf16 v[52:55], v[246:249], v[96:99], v[52:55]
	v_mfma_f32_16x16x32_bf16 v[48:51], v[246:249], v[80:83], v[48:51]
	s_waitcnt lgkmcnt(6)
	v_mfma_f32_16x16x32_bf16 v[44:47], v[162:165], v[92:95], v[44:47]
	v_mfma_f32_16x16x32_bf16 v[40:43], v[162:165], v[76:79], v[40:43]
	v_mfma_f32_16x16x32_bf16 v[44:47], v[166:169], v[96:99], v[44:47]
	v_mfma_f32_16x16x32_bf16 v[40:43], v[166:169], v[80:83], v[40:43]
	s_waitcnt lgkmcnt(2)
	v_mfma_f32_16x16x32_bf16 v[36:39], v[170:173], v[92:95], v[36:39]
	v_mfma_f32_16x16x32_bf16 v[32:35], v[170:173], v[76:79], v[32:35]
	v_mfma_f32_16x16x32_bf16 v[36:39], v[174:177], v[96:99], v[36:39]
	v_mfma_f32_16x16x32_bf16 v[32:35], v[174:177], v[80:83], v[32:35]
	v_mfma_f32_16x16x32_bf16 v[28:31], v[250:253], v[92:95], v[28:31]
	v_mfma_f32_16x16x32_bf16 v[24:27], v[250:253], v[76:79], v[24:27]
	v_mfma_f32_16x16x32_bf16 v[28:31], v[250:253], v[96:99], v[28:31]
	v_mfma_f32_16x16x32_bf16 v[24:27], v[250:253], v[80:83], v[24:27]
	v_add3_u32 v104, s10, v110, v142
	v_add3_u32 v147, s10, v138, v143
	v_lshl_add_u64 v[132:133], v[132:133], 0, s[50:51]
	v_lshl_add_u64 v[134:135], v[134:135], 0, s[4:5]
	v_lshl_add_u64 v[136:137], v[136:137], 0, s[4:5]
	s_cmp_eq_u32 s6, s7
	s_waitcnt lgkmcnt(0)
	s_cbranch_scc0 .LBB0_175
	s_barrier
	s_branch .LBB0_161
.Lattn_refresh:
	s_waitcnt lgkmcnt(9)
	v_mfma_f32_16x16x32_bf16 v[92:95], v[162:165], v[0:3], 0
	v_mfma_f32_16x16x32_bf16 v[76:79], v[162:165], v[8:11], 0
	ds_read_b64 v[234:235], v147 offset:14336
	ds_read_b64 v[236:237], v147 offset:14368
	v_mfma_f32_16x16x32_bf16 v[92:95], v[166:169], v[4:7], v[92:95]
	v_mfma_f32_16x16x32_bf16 v[76:79], v[166:169], v[12:15], v[76:79]
	ds_read_b64 v[238:239], v147 offset:14400
	ds_read_b64 v[240:241], v147 offset:14432
	v_mfma_f32_16x16x32_bf16 v[92:95], v[170:173], v[16:19], v[92:95]
	v_mfma_f32_16x16x32_bf16 v[76:79], v[170:173], v[20:23], v[76:79]
	ds_read_b64 v[242:243], v147 offset:16640
	ds_read_b64 v[244:245], v147 offset:16672
	s_waitcnt lgkmcnt(12)
	v_mfma_f32_16x16x32_bf16 v[96:99], v[174:177], v[0:3], 0
	v_mfma_f32_16x16x32_bf16 v[80:83], v[174:177], v[8:11], 0
	ds_read_b64 v[246:247], v147 offset:16704
	v_mfma_f32_16x16x32_bf16 v[96:99], v[178:181], v[4:7], v[96:99]
	v_mfma_f32_16x16x32_bf16 v[80:83], v[178:181], v[12:15], v[80:83]
	ds_read_b64 v[248:249], v147 offset:16736
	v_mfma_f32_16x16x32_bf16 v[96:99], v[182:185], v[16:19], v[96:99]
	v_mfma_f32_16x16x32_bf16 v[80:83], v[182:185], v[20:23], v[80:83]
	ds_read_b64 v[162:163], v147 offset:18944
	s_waitcnt lgkmcnt(12)
	v_mfma_f32_16x16x32_bf16 v[100:103], v[186:189], v[0:3], 0
	v_mfma_f32_16x16x32_bf16 v[84:87], v[186:189], v[8:11], 0
	ds_read_b64 v[164:165], v147 offset:18976
	v_mfma_f32_16x16x32_bf16 v[100:103], v[214:217], v[4:7], v[100:103]
	v_mfma_f32_16x16x32_bf16 v[84:87], v[214:217], v[12:15], v[84:87]
	ds_read_b64 v[166:167], v147 offset:19008
	v_mfma_f32_16x16x32_bf16 v[100:103], v[218:221], v[16:19], v[100:103]
	v_mfma_f32_16x16x32_bf16 v[84:87], v[218:221], v[20:23], v[84:87]
	ds_read_b64 v[168:169], v147 offset:19040
	s_waitcnt lgkmcnt(12)
	v_mfma_f32_16x16x32_bf16 v[104:107], v[222:225], v[0:3], 0
	v_mfma_f32_16x16x32_bf16 v[88:91], v[222:225], v[8:11], 0
	ds_read_b64 v[170:171], v147 offset:21248
	v_mfma_f32_16x16x32_bf16 v[104:107], v[226:229], v[4:7], v[104:107]
	v_mfma_f32_16x16x32_bf16 v[88:91], v[226:229], v[12:15], v[88:91]
	ds_read_b64 v[172:173], v147 offset:21280
	v_mfma_f32_16x16x32_bf16 v[104:107], v[230:233], v[16:19], v[104:107]
	v_mfma_f32_16x16x32_bf16 v[88:91], v[230:233], v[20:23], v[88:91]
	s_waitcnt lgkmcnt(13)
	ds_read_b64 v[174:175], v147 offset:21312
	ds_read_b64 v[176:177], v147 offset:21344
	s_nop 7
	v_max_f32_e32 v127, v93, v93
	v_max_f32_e32 v129, v92, v92
	v_max_f32_e32 v127, v129, v127
	v_max_f32_e32 v129, v95, v95
	v_max_f32_e32 v131, v94, v94
	v_max_f32_e32 v129, v131, v129
	v_max_f32_e32 v131, v99, v99
	v_max_f32_e32 v147, v98, v98
	v_max_f32_e32 v131, v147, v131
	v_max3_f32 v131, v96, v97, v131
	v_max3_f32 v127, v127, v129, v131
	v_max_f32_e32 v129, v103, v103
	v_max_f32_e32 v131, v102, v102
	v_max_f32_e32 v129, v131, v129
	v_max_f32_e32 v131, v107, v107
	v_max_f32_e32 v147, v106, v106
	v_max_f32_e32 v131, v147, v131
	v_max3_f32 v129, v100, v101, v129
	v_max3_f32 v131, v104, v105, v131
	v_max3_f32 v127, v127, v129, v131
	ds_bpermute_b32 v129, v145, v127
	s_waitcnt lgkmcnt(0)
	v_max_f32_e32 v129, v129, v129
	v_max_f32_e32 v127, v127, v129
	ds_bpermute_b32 v129, v144, v127
	s_waitcnt lgkmcnt(0)
	v_max3_f32 v127, v130, v127, v129
	v_sub_f32_e32 v129, v130, v127
	v_exp_f32_e32 v130, v129
	s_nop 0
	v_pk_mul_f32 v[62:63], v[62:63], v[130:131] op_sel_hi:[1,0]
	v_pk_mul_f32 v[60:61], v[60:61], v[130:131] op_sel_hi:[1,0]
	v_pk_mul_f32 v[54:55], v[54:55], v[130:131] op_sel_hi:[1,0]
	v_pk_mul_f32 v[52:53], v[52:53], v[130:131] op_sel_hi:[1,0]
	v_pk_mul_f32 v[46:47], v[46:47], v[130:131] op_sel_hi:[1,0]
	v_pk_mul_f32 v[44:45], v[44:45], v[130:131] op_sel_hi:[1,0]
	v_pk_mul_f32 v[38:39], v[38:39], v[130:131] op_sel_hi:[1,0]
	v_pk_mul_f32 v[36:37], v[36:37], v[130:131] op_sel_hi:[1,0]
	v_pk_mul_f32 v[30:31], v[30:31], v[130:131] op_sel_hi:[1,0]
	v_pk_mul_f32 v[28:29], v[28:29], v[130:131] op_sel_hi:[1,0]
	v_mov_b32_e32 v130, v127
	v_xor_b32_e32 v148, 0x80000000, v127
	v_xor_b32_e32 v149, 0x80000000, v127
	v_xor_b32_e32 v150, 0x80000000, v127
	v_xor_b32_e32 v151, 0x80000000, v127
	v_max_f32_e32 v127, v77, v77
	v_max_f32_e32 v129, v76, v76
	v_max_f32_e32 v127, v129, v127
	v_max_f32_e32 v129, v79, v79
	v_max_f32_e32 v131, v78, v78
	v_max_f32_e32 v129, v131, v129
	v_max_f32_e32 v131, v83, v83
	v_max_f32_e32 v147, v82, v82
	v_max_f32_e32 v131, v147, v131
	v_max3_f32 v131, v80, v81, v131
	v_max3_f32 v127, v127, v129, v131
	v_max_f32_e32 v129, v87, v87
	v_max_f32_e32 v131, v86, v86
	v_max_f32_e32 v129, v131, v129
	v_max_f32_e32 v131, v91, v91
	v_max_f32_e32 v147, v90, v90
	v_max_f32_e32 v131, v147, v131
	v_max3_f32 v129, v84, v85, v129
	v_max3_f32 v131, v88, v89, v131
	v_max3_f32 v127, v127, v129, v131
	ds_bpermute_b32 v129, v145, v127
	s_waitcnt lgkmcnt(0)
	v_max_f32_e32 v129, v129, v129
	v_max_f32_e32 v127, v127, v129
	ds_bpermute_b32 v129, v144, v127
	s_waitcnt lgkmcnt(0)
	v_max3_f32 v131, v128, v127, v129
	v_sub_f32_e32 v127, v128, v131
	v_exp_f32_e32 v128, v127
	s_nop 0
	v_pk_mul_f32 v[58:59], v[58:59], v[128:129] op_sel_hi:[1,0]
	v_pk_mul_f32 v[56:57], v[56:57], v[128:129] op_sel_hi:[1,0]
	v_pk_mul_f32 v[50:51], v[50:51], v[128:129] op_sel_hi:[1,0]
	v_pk_mul_f32 v[48:49], v[48:49], v[128:129] op_sel_hi:[1,0]
	v_pk_mul_f32 v[42:43], v[42:43], v[128:129] op_sel_hi:[1,0]
	v_pk_mul_f32 v[40:41], v[40:41], v[128:129] op_sel_hi:[1,0]
	v_pk_mul_f32 v[34:35], v[34:35], v[128:129] op_sel_hi:[1,0]
	v_pk_mul_f32 v[32:33], v[32:33], v[128:129] op_sel_hi:[1,0]
	v_pk_mul_f32 v[26:27], v[26:27], v[128:129] op_sel_hi:[1,0]
	v_pk_mul_f32 v[24:25], v[24:25], v[128:129] op_sel_hi:[1,0]
	v_mov_b32_e32 v128, v131
	v_xor_b32_e32 v152, 0x80000000, v131
	v_xor_b32_e32 v153, 0x80000000, v131
	v_xor_b32_e32 v154, 0x80000000, v131
	v_xor_b32_e32 v155, 0x80000000, v131
	v_pk_add_f32 v[92:93], v[92:93], v[130:131] op_sel_hi:[1,0] neg_lo:[0,1] neg_hi:[0,1]
	v_pk_add_f32 v[94:95], v[94:95], v[130:131] op_sel_hi:[1,0] neg_lo:[0,1] neg_hi:[0,1]
	v_pk_add_f32 v[96:97], v[96:97], v[130:131] op_sel_hi:[1,0] neg_lo:[0,1] neg_hi:[0,1]
	v_pk_add_f32 v[98:99], v[98:99], v[130:131] op_sel_hi:[1,0] neg_lo:[0,1] neg_hi:[0,1]
	v_pk_add_f32 v[100:101], v[100:101], v[130:131] op_sel_hi:[1,0] neg_lo:[0,1] neg_hi:[0,1]
	v_pk_add_f32 v[102:103], v[102:103], v[130:131] op_sel_hi:[1,0] neg_lo:[0,1] neg_hi:[0,1]
	v_pk_add_f32 v[104:105], v[104:105], v[130:131] op_sel_hi:[1,0] neg_lo:[0,1] neg_hi:[0,1]
	v_pk_add_f32 v[106:107], v[106:107], v[130:131] op_sel_hi:[1,0] neg_lo:[0,1] neg_hi:[0,1]
	v_pk_add_f32 v[76:77], v[76:77], v[128:129] op_sel_hi:[1,0] neg_lo:[0,1] neg_hi:[0,1]
	v_pk_add_f32 v[78:79], v[78:79], v[128:129] op_sel_hi:[1,0] neg_lo:[0,1] neg_hi:[0,1]
	v_pk_add_f32 v[80:81], v[80:81], v[128:129] op_sel_hi:[1,0] neg_lo:[0,1] neg_hi:[0,1]
	v_pk_add_f32 v[82:83], v[82:83], v[128:129] op_sel_hi:[1,0] neg_lo:[0,1] neg_hi:[0,1]
	v_pk_add_f32 v[84:85], v[84:85], v[128:129] op_sel_hi:[1,0] neg_lo:[0,1] neg_hi:[0,1]
	v_pk_add_f32 v[86:87], v[86:87], v[128:129] op_sel_hi:[1,0] neg_lo:[0,1] neg_hi:[0,1]
	v_pk_add_f32 v[88:89], v[88:89], v[128:129] op_sel_hi:[1,0] neg_lo:[0,1] neg_hi:[0,1]
	v_pk_add_f32 v[90:91], v[90:91], v[128:129] op_sel_hi:[1,0] neg_lo:[0,1] neg_hi:[0,1]
	s_branch .Lattn_sm
